# k0 key loop: one workgroup barrier per key tile (waves 0-3 run X,Y between barriers, waves 4-7 run Y,X); was two barriers per tile
# speedup vs baseline: 1.0046x; 1.0046x over previous
; template <int DV> ...
;     ...
;         const int k0 = (t < n0) ? (s0a + (t << 6)) : (s1a + ((t - n0) << 6));
;         const bool more = (t + 1 < nt);
;         if (more) {
;             const int k1 = (t + 1 < n0) ? (s0a + ((t + 1) << 6)) : (s1a + ((t + 1 - n0) << 6));
;             kr = *(const u32x4*)(kg + (size_t)k1 * kpitch); vr0 = *(const u32x4*)(vg + k1);
;             if (DV == 128) vr1 = *(const u32x4*)(vg + (size_t)64 * NKV + k1);
;         }
;         const LAS unsigned char* Kl = lds + (t & 1) * ABUFB;
;         const LAS unsigned char* Vl = Kl + KBUFB;
;         const bool masked = win && (t < n0);
;         const bool skip = masked && ((k0 + 63 < qw0 - 128) || (k0 > qw0 + 31 + 128));
;         if (!skip) {
;             f32x16 p0, p1;
;             {
;                 bf16x8 kf[8];
; #pragma unroll
;                 for (int d0 = 0; d0 < 4; ++d0) {
;                     kf[2 * d0] = *(const LAS bf16x8*)(Kl + (r32 * KP + 16 * d0 + 8 * hi) * 2);
;                     kf[2 * d0 + 1] = *(const LAS bf16x8*)(Kl + ((32 + r32) * KP + 16 * d0 + 8 * hi) * 2);
;                 }
;                 __builtin_amdgcn_sched_barrier(0);
;                 p0 = __builtin_amdgcn_mfma_f32_32x32x16_bf16(kf[0], qf[0], negm, 0, 0, 0); p1 = __builtin_amdgcn_mfma_f32_32x32x16_bf16(kf[1], qf[0], negm, 0, 0, 0);
; #pragma unroll
;                 for (int d0 = 1; d0 < 4; ++d0) { p0 = __builtin_amdgcn_mfma_f32_32x32x16_bf16(kf[2 * d0], qf[d0], p0, 0, 0, 0); p1 = __builtin_amdgcn_mfma_f32_32x32x16_bf16(kf[2 * d0 + 1], qf[d0], p1, 0, 0, 0); }
;                 __builtin_amdgcn_sched_barrier(0);
;             }
;     ...
; #pragma unroll
;                 for (int db = 0; db < 2; ++db)
; #pragma unroll
;                     for (int c = 0; c < 4; ++c) {
;                         o[db] = __builtin_amdgcn_mfma_f32_32x32x16_bf16(vfa[db * 4 + c], pk[c], o[db], 0, 0, 0);
;                     }
;                 __builtin_amdgcn_sched_barrier(0);
; #pragma unroll
;                 for (int db = 2; db < DV / 32; ++db)
; #pragma unroll
;                     for (int c = 0; c < 4; ++c) {
;                         o[db] = __builtin_amdgcn_mfma_f32_32x32x16_bf16(vfb[(db - 2) * 4 + c], pk[c], o[db], 0, 0, 0);
;                     }
;             } else {
; #pragma unroll
;                 for (int db = 0; db < 2; ++db)
; #pragma unroll
;                     for (int c = 0; c < 4; ++c) {
.Lpa_pre_done:
	v_readfirstlane_b32 s25, v253
	s_lshr_b32 s25, s25, 8
	s_mov_b32 s22, 0
.Lpa_X:
	s_setprio 1
	s_and_b32 s4, s22, 1
	s_mul_i32 s23, s4, 0x6c00
	s_sub_i32 s24, 0x6c00, s23
	v_add_u32_e32 v199, s23, v194
	s_add_i32 s3, s22, 1
	s_mul_hi_u32 s4, s3, 0x55555556
	s_mul_i32 s4, s4, 3
	s_sub_i32 s4, s3, s4
	s_mul_i32 s5, s4, 0x6c00
	v_add_u32_e32 v218, s24, v192
	v_add_u32_e32 v219, s5, v193
	s_branch .Lpa_Xfirst
.Lpa_X2:
	s_setprio 1
	s_cmp_ge_i32 s22, s26
	s_cbranch_scc1 .Lpa_Xlast
	s_waitcnt lgkmcnt(11)
	v_mfma_f32_32x32x16_bf16 v[2:17], v[82:85], v[200:203], v[2:17]
	ds_read_b128 v[158:161], v197 offset:23040
	s_waitcnt lgkmcnt(11)
	v_mfma_f32_32x32x16_bf16 v[2:17], v[86:89], v[204:207], v[2:17]
	ds_read_b128 v[162:165], v197 offset:23072
	s_waitcnt lgkmcnt(11)
	v_mfma_f32_32x32x16_bf16 v[2:17], v[90:93], v[210:213], v[2:17]
	ds_read_b128 v[166:169], v197 offset:23104
	s_waitcnt lgkmcnt(11)
	v_mfma_f32_32x32x16_bf16 v[2:17], v[94:97], v[214:217], v[2:17]
	ds_read_b128 v[170:173], v197 offset:23136
	s_waitcnt vmcnt(0)
	s_waitcnt lgkmcnt(11)
	v_mfma_f32_32x32x16_bf16 v[18:33], v[98:101], v[200:203], v[18:33]
	ds_write_b128 v218, v[130:133]
	s_waitcnt lgkmcnt(11)
	v_mfma_f32_32x32x16_bf16 v[18:33], v[102:105], v[204:207], v[18:33]
	ds_write_b128 v219, v[134:137] offset:9216
	s_waitcnt lgkmcnt(11)
	v_mfma_f32_32x32x16_bf16 v[18:33], v[106:109], v[210:213], v[18:33]
	ds_write_b128 v219, v[138:141] offset:18432
	s_waitcnt lgkmcnt(11)
	v_mfma_f32_32x32x16_bf16 v[18:33], v[110:113], v[214:217], v[18:33]
	s_add_i32 s3, s22, 2
	s_add_i32 s4, s26, -1
	s_min_i32 s3, s3, s4
	s_cmp_lt_i32 s3, s1
	s_cselect_b32 s4, 0, s1
	s_cselect_b32 s5, s94, 0x2000
	s_sub_i32 s4, s3, s4
	s_lshl_b32 s4, s4, 6
	s_add_i32 s4, s5, s4
	s_ashr_i32 s5, s4, 31
	s_lshl_b64 s[30:31], s[4:5], 10
	v_lshl_add_u64 v[218:219], v[180:181], 0, s[30:31]
	s_lshl_b64 s[30:31], s[4:5], 1
	v_lshl_add_u64 v[220:221], v[182:183], 0, s[30:31]
	s_waitcnt lgkmcnt(10)
	v_mfma_f32_32x32x16_bf16 v[50:65], v[142:145], v[200:203], v[50:65]
	ds_read_b128 v[142:145], v199
	global_load_dwordx4 v[130:133], v[218:219], off
	s_waitcnt lgkmcnt(10)
	v_mfma_f32_32x32x16_bf16 v[50:65], v[146:149], v[204:207], v[50:65]
	ds_read_b128 v[146:149], v199 offset:4608
	global_load_dwordx4 v[134:137], v[220:221], off
	s_waitcnt lgkmcnt(10)
	v_mfma_f32_32x32x16_bf16 v[50:65], v[150:153], v[210:213], v[50:65]
	ds_read_b128 v[150:153], v199 offset:32
	v_lshl_add_u64 v[218:219], v[186:187], 0, s[30:31]
	s_waitcnt lgkmcnt(10)
	v_mfma_f32_32x32x16_bf16 v[50:65], v[154:157], v[214:217], v[50:65]
	ds_read_b128 v[154:157], v199 offset:4640
	global_load_dwordx4 v[138:141], v[218:219], off
	s_waitcnt lgkmcnt(10)
	v_mfma_f32_32x32x16_bf16 v[34:49], v[158:161], v[200:203], v[34:49]
	ds_read_b128 v[158:161], v199 offset:64
	s_waitcnt lgkmcnt(10)
	v_mfma_f32_32x32x16_bf16 v[34:49], v[162:165], v[204:207], v[34:49]
	ds_read_b128 v[162:165], v199 offset:4672
	s_waitcnt lgkmcnt(10)
	v_mfma_f32_32x32x16_bf16 v[34:49], v[166:169], v[210:213], v[34:49]
	ds_read_b128 v[166:169], v199 offset:96
	s_waitcnt lgkmcnt(10)
	v_mfma_f32_32x32x16_bf16 v[34:49], v[170:173], v[214:217], v[34:49]
	ds_read_b128 v[170:173], v199 offset:4704
	s_waitcnt lgkmcnt(7)
	v_mfma_f32_32x32x16_bf16 v[98:113], v[142:145], v[126:129], v[66:81]
	s_waitcnt lgkmcnt(5)
	v_mfma_f32_32x32x16_bf16 v[98:113], v[150:153], v[122:125], v[98:113]
	s_waitcnt lgkmcnt(3)
	v_mfma_f32_32x32x16_bf16 v[98:113], v[158:161], v[118:121], v[98:113]
	s_waitcnt lgkmcnt(1)
	v_mfma_f32_32x32x16_bf16 v[98:113], v[166:169], v[114:117], v[98:113]
	v_mfma_f32_32x32x16_bf16 v[82:97], v[146:149], v[126:129], v[66:81]
	v_mfma_f32_32x32x16_bf16 v[82:97], v[154:157], v[122:125], v[82:97]
	v_mfma_f32_32x32x16_bf16 v[82:97], v[162:165], v[118:121], v[82:97]
	s_waitcnt lgkmcnt(0)
	v_mfma_f32_32x32x16_bf16 v[82:97], v[170:173], v[114:117], v[82:97]
	s_cmp_eq_u32 s25, 0
	s_cbranch_scc1 .Lpa_Y
	s_barrier
	s_branch .Lpa_Y

; #define LAS __attribute__((address_space(3)))
; template <int DV> ...
;     ...
;         if (more) {
;             const unsigned bo = ((t + 1) & 1) * ABUFB;
;             *(LAS u32x4*)(lds + bo + kst) = kr;
;             *(LAS u32x4*)(lds + bo + vst) = vr0;
;             if (DV == 128) *(LAS u32x4*)(lds + bo + vst + 64 * VP * 2) = vr1;
;         }
;         __syncthreads();
.Lpa_noload_first:
	s_waitcnt lgkmcnt(0)
	s_cmp_eq_u32 s25, 0
	s_cbranch_scc1 .Lpa_Y
	s_barrier

; #define LAS __attribute__((address_space(3)))
; template <int DV> ...
;     ...
;             bf16x8 vfa[8];
; #pragma unroll
;             for (int db = 0; db < 2; ++db)
; #pragma unroll
;                 for (int c = 0; c < 4; ++c) vfa[db * 4 + c] = *(const LAS bf16x8*)(Vl + ((32 * db + r32) * VP + 16 * c + 8 * hi) * 2);
;     ...
;             lrun += rs0 + rs1;
;     ...
;                 for (int db = 2; db < 4; ++db)
; #pragma unroll
;                     for (int c = 0; c < 4; ++c) vfb[(db - 2) * 4 + c] = *(const LAS bf16x8*)(Vl + ((32 * db + r32) * VP + 16 * c + 8 * hi) * 2);
.Lpa_tail:
	v_add_f32_e32 v189, v189, v198
	s_mul_hi_u32 s4, s22, 0x55555556
	s_mul_i32 s4, s4, 3
	s_sub_i32 s4, s22, s4
	s_mul_i32 s4, s4, 0x6c00
	v_add3_u32 v197, s4, v0, v196
	ds_read_b128 v[82:85], v197 offset:9216
	ds_read_b128 v[86:89], v197 offset:9248
	ds_read_b128 v[90:93], v197 offset:9280
	ds_read_b128 v[94:97], v197 offset:9312
	ds_read_b128 v[98:101], v197 offset:13824
	ds_read_b128 v[102:105], v197 offset:13856
	ds_read_b128 v[106:109], v197 offset:13888
	ds_read_b128 v[110:113], v197 offset:13920
	ds_read_b128 v[142:145], v197 offset:18432
	ds_read_b128 v[146:149], v197 offset:18464
	ds_read_b128 v[150:153], v197 offset:18496
	ds_read_b128 v[154:157], v197 offset:18528
	s_add_i32 s22, s22, 1
	s_and_b32 s4, s22, 1
	s_mul_i32 s23, s4, 0x6c00
	s_sub_i32 s24, 0x6c00, s23
	v_add_u32_e32 v199, s23, v194
	s_add_i32 s3, s22, 1
	s_mul_hi_u32 s4, s3, 0x55555556
	s_mul_i32 s4, s4, 3
	s_sub_i32 s4, s3, s4
	s_mul_i32 s5, s4, 0x6c00
	v_add_u32_e32 v218, s24, v192
	v_add_u32_e32 v219, s5, v193
	s_cmp_lg_u32 s25, 0
	s_cbranch_scc1 .Lpa_X2
	s_barrier
	s_branch .Lpa_X2

; template <int DV> ...
;     ...
; #pragma unroll
;                 for (int db = 0; db < 2; ++db)
; #pragma unroll
;                     for (int c = 0; c < 4; ++c) {
;                         o[db] = __builtin_amdgcn_mfma_f32_32x32x16_bf16(vfa[db * 4 + c], pk[c], o[db], 0, 0, 0);
;                     }
;                 __builtin_amdgcn_sched_barrier(0);
; #pragma unroll
;                 for (int db = 2; db < DV / 32; ++db)
; #pragma unroll
;                     for (int c = 0; c < 4; ++c) {
;                         o[db] = __builtin_amdgcn_mfma_f32_32x32x16_bf16(vfb[(db - 2) * 4 + c], pk[c], o[db], 0, 0, 0);
;                     }
;     ...
;         __syncthreads();
.Lpa_Xlast:
	s_waitcnt lgkmcnt(11)
	v_mfma_f32_32x32x16_bf16 v[2:17], v[82:85], v[200:203], v[2:17]
	ds_read_b128 v[158:161], v197 offset:23040
	s_waitcnt lgkmcnt(11)
	v_mfma_f32_32x32x16_bf16 v[2:17], v[86:89], v[204:207], v[2:17]
	ds_read_b128 v[162:165], v197 offset:23072
	s_waitcnt lgkmcnt(11)
	v_mfma_f32_32x32x16_bf16 v[2:17], v[90:93], v[210:213], v[2:17]
	ds_read_b128 v[166:169], v197 offset:23104
	s_waitcnt lgkmcnt(11)
	v_mfma_f32_32x32x16_bf16 v[2:17], v[94:97], v[214:217], v[2:17]
	ds_read_b128 v[170:173], v197 offset:23136
	s_waitcnt lgkmcnt(11)
	v_mfma_f32_32x32x16_bf16 v[18:33], v[98:101], v[200:203], v[18:33]
	s_waitcnt lgkmcnt(10)
	v_mfma_f32_32x32x16_bf16 v[18:33], v[102:105], v[204:207], v[18:33]
	s_waitcnt lgkmcnt(9)
	v_mfma_f32_32x32x16_bf16 v[18:33], v[106:109], v[210:213], v[18:33]
	s_waitcnt lgkmcnt(8)
	v_mfma_f32_32x32x16_bf16 v[18:33], v[110:113], v[214:217], v[18:33]
	s_waitcnt lgkmcnt(7)
	v_mfma_f32_32x32x16_bf16 v[50:65], v[142:145], v[200:203], v[50:65]
	s_waitcnt lgkmcnt(6)
	v_mfma_f32_32x32x16_bf16 v[50:65], v[146:149], v[204:207], v[50:65]
	s_waitcnt lgkmcnt(5)
	v_mfma_f32_32x32x16_bf16 v[50:65], v[150:153], v[210:213], v[50:65]
	s_waitcnt lgkmcnt(4)
	v_mfma_f32_32x32x16_bf16 v[50:65], v[154:157], v[214:217], v[50:65]
	s_waitcnt lgkmcnt(3)
	v_mfma_f32_32x32x16_bf16 v[34:49], v[158:161], v[200:203], v[34:49]
	s_waitcnt lgkmcnt(2)
	v_mfma_f32_32x32x16_bf16 v[34:49], v[162:165], v[204:207], v[34:49]
	s_waitcnt lgkmcnt(1)
	v_mfma_f32_32x32x16_bf16 v[34:49], v[166:169], v[210:213], v[34:49]
	s_waitcnt lgkmcnt(0)
	v_mfma_f32_32x32x16_bf16 v[34:49], v[170:173], v[214:217], v[34:49]
	s_setprio 0
	s_barrier
.Lpa_done:
.LBB0_436:
	v_mov_b32_e32 v69, v185
